# adds: scan gate-load prefetch in mlstm_scan; P7 workgroups 64..159 run the k/v window copy before their tile
# speedup vs baseline: 1.0022x; 1.0022x over previous
; #define REPS(k) for (int rep_ = 0; rep_ < 1 + ((REPMASK >> (k)) & 1); ++rep_, (((REPMASK >> (k)) & 1) && rep_ == 1 ? grid.sync() : (void)0))
; __global__ void __launch_bounds__(512, 2) fwd_mega(Params prm) {
;     ...
;     if (IN(7)) REPS(7) { pg8::Gemm g{(const bf16_t*)(ws + WS_MIX), (const bf16_t*)(ws + WS_WOUT), D, D}; pg8::PromptSampleOrder S{F.G, F.bid, D / 64, 4};
;         pg8::EpiRes E{(float*)(ws + WS_X1), F.in[0], F.in[1], mod + 4096, (float*)(ws + WS_PART)}; pg8::gemm_phase(F.lds, g, S, E);
;         if (F.G == 256) { if (F.bid >= 64) kvwin_copy(F, (F.bid - 64) * 512 + F.tid, (F.G - 64) * 512); } else kvwin_copy(F, F.bid * 512 + F.tid, F.G * 512); }
.LBB0_857:
	s_cmp_lt_i32 s86, 8
	s_cselect_b64 s[2:3], -1, 0
	s_and_b64 s[4:5], s[2:3], s[0:1]
	s_andn2_b64 vcc, exec, s[4:5]
	s_cbranch_vccnz .LBB0_912
	s_mov_b32 s98, 0
	s_cmpk_lt_i32 s33, 64
	s_cbranch_scc1 .Lmy_p7_go
	s_cmpk_gt_i32 s33, 159
	s_cbranch_scc1 .Lmy_p7_go
	s_cmpk_lg_i32 s88, 0x100
	s_cbranch_scc1 .Lmy_p7_go
	s_mov_b32 s98, 1
	s_branch .LBB0_901
.Lmy_p7_go:
	s_cmpk_gt_i32 s33, 0x13f
	v_readfirstlane_b32 s16, v144
	s_cbranch_scc0 .LBB0_861
	s_cmpk_lg_i32 s88, 0x100
	s_mov_b64 s[0:1], -1
	s_cbranch_scc1 .LBB0_891

; __device__ __forceinline__ void kvwin_copy(const Frame& F, int gt, int GT) {
;     const int per = 124 * 64;
;     for (int i0 = gt; i0 < NB * per; i0 += 4 * GT) { f32x4 a[4], b[4]; size_t so[4], dof[4];
; #pragma unroll
;         for (int u = 0; u < 4; ++u) { const int i = i0 + u * GT; const int ii = i < NB * per ? i : 0; const int bb = ii / per, o = ii - bb * per; so[u] = (size_t)bb * 8192 + 256 + o; dof[u] = (size_t)bb * 8192 + o;
; __global__ void __launch_bounds__(512, 2) fwd_mega(Params prm) {
;     ...
;         if (F.G == 256) { if (F.bid >= 64) kvwin_copy(F, (F.bid - 64) * 512 + F.tid, (F.G - 64) * 512); } else kvwin_copy(F, F.bid * 512 + F.tid, F.G * 512); }
.LBB0_901:
	s_cmp_eq_u32 s98, 2
	s_cbranch_scc1 .LBB0_912
	s_cmp_lt_i32 s33, 64
	s_cbranch_scc1 .LBB0_912
	s_lshl_b32 s0, s33, 9
	s_addk_i32 s0, 0x8000
	v_add_u32_e32 v38, s0, v144
	s_mov_b32 s0, 0xf8000
	v_cmp_gt_i32_e32 vcc, s0, v38
	s_and_saveexec_b64 s[6:7], vcc
	s_cbranch_execz .LBB0_911
	v_readlane_b32 s8, v245, 21
	v_readlane_b32 s14, v245, 27
	v_readlane_b32 s15, v245, 28
	v_readlane_b32 s22, v245, 35
	v_readlane_b32 s23, v245, 36
	s_mov_b64 s[14:15], s[22:23]
	v_readlane_b32 s9, v245, 22
	s_add_u32 s8, s14, 0x4541010
	v_readlane_b32 s10, v245, 23
	s_addc_u32 s9, s15, 0
	v_readlane_b32 s11, v245, 24
	v_readlane_b32 s12, v245, 25
	v_readlane_b32 s13, v245, 26
	v_readlane_b32 s18, v245, 31
	v_readlane_b32 s19, v245, 32
	v_readlane_b32 s20, v245, 33
	v_readlane_b32 s21, v245, 34
	s_add_u32 s10, s14, 0x5541010
	s_addc_u32 s11, s15, 0
	s_mov_b64 s[12:13], 0
	s_mov_b32 s18, 0xe0000
	s_mov_b32 s19, 0x84210843
	s_movk_i32 s20, 0xe100
	s_mov_b64 s[14:15], 0x1000
	s_waitcnt vmcnt(0)
	v_mov_b64_e32 v[24:25], 0x1000
	s_mov_b32 s21, 0xc8000
	s_mov_b32 s22, 0xb0000
	s_mov_b32 s23, 0x97fff
	v_readlane_b32 s16, v245, 29
	v_readlane_b32 s17, v245, 30
	s_branch .LBB0_905

; __device__ __forceinline__ void kvwin_copy(const Frame& F, int gt, int GT) {
;     ...
;         for (int u = 0; u < 4; ++u) { if (i0 + u * GT < NB * per) { __builtin_nontemporal_store(a[u], (f32x4*)(F.out + O_KWS) + dof[u]); __builtin_nontemporal_store(b[u], (f32x4*)(F.out + O_VWS) + dof[u]); } } }
; }
; __global__ void __launch_bounds__(512, 2) fwd_mega(Params prm) {
;     ...
;         if (F.G == 256) { if (F.bid >= 64) kvwin_copy(F, (F.bid - 64) * 512 + F.tid, (F.G - 64) * 512); } else kvwin_copy(F, F.bid * 512 + F.tid, F.G * 512); }
.LBB0_911:
	s_or_b64 exec, exec, s[6:7]
	s_cmp_eq_u32 s98, 1
	s_cbranch_scc0 .LBB0_912
	s_mov_b32 s98, 2
	s_branch .Lmy_p7_go

; __global__ void __launch_bounds__(512, 2) fwd_mega(Params prm) {
	.amdhsa_kernel _Z8fwd_mega6Params
		.amdhsa_group_segment_fixed_size 0
		.amdhsa_private_segment_fixed_size 0
		.amdhsa_kernarg_size 472
		.amdhsa_user_sgpr_count 2
		.amdhsa_user_sgpr_dispatch_ptr 0
		.amdhsa_user_sgpr_queue_ptr 0
		.amdhsa_user_sgpr_kernarg_segment_ptr 1
		.amdhsa_user_sgpr_dispatch_id 0
		.amdhsa_user_sgpr_kernarg_preload_length 0
		.amdhsa_user_sgpr_kernarg_preload_offset 0
		.amdhsa_user_sgpr_private_segment_size 0
		.amdhsa_uses_dynamic_stack 0
		.amdhsa_enable_private_segment 0
		.amdhsa_system_sgpr_workgroup_id_x 1
		.amdhsa_system_sgpr_workgroup_id_y 0
		.amdhsa_system_sgpr_workgroup_id_z 0
		.amdhsa_system_sgpr_workgroup_info 0
		.amdhsa_system_vgpr_workitem_id 2
		.amdhsa_next_free_vgpr 246
		.amdhsa_next_free_sgpr 102
		.amdhsa_accum_offset 248
		.amdhsa_reserve_vcc 1
		.amdhsa_float_round_mode_32 0
		.amdhsa_float_round_mode_16_64 0
		.amdhsa_float_denorm_mode_32 3
		.amdhsa_float_denorm_mode_16_64 3
		.amdhsa_dx10_clamp 1
		.amdhsa_ieee_mode 1
		.amdhsa_fp16_overflow 0
		.amdhsa_tg_split 0
		.amdhsa_exception_fp_ieee_invalid_op 0
		.amdhsa_exception_fp_denorm_src 0
		.amdhsa_exception_fp_ieee_div_zero 0
		.amdhsa_exception_fp_ieee_overflow 0
		.amdhsa_exception_fp_ieee_underflow 0
		.amdhsa_exception_fp_ieee_inexact 0
		.amdhsa_exception_int_div_zero 0
	.end_amdhsa_kernel

; __global__ void __launch_bounds__(512, 2) fwd_mega(Params prm) {
amdhsa.kernels:
  - .agpr_count:     0
    .args:
      - .offset:         0
        .size:           216
        .value_kind:     by_value
      - .offset:         216
        .size:           4
        .value_kind:     hidden_block_count_x
      - .offset:         220
        .size:           4
        .value_kind:     hidden_block_count_y
      - .offset:         224
        .size:           4
        .value_kind:     hidden_block_count_z
      - .offset:         228
        .size:           2
        .value_kind:     hidden_group_size_x
      - .offset:         230
        .size:           2
        .value_kind:     hidden_group_size_y
      - .offset:         232
        .size:           2
        .value_kind:     hidden_group_size_z
      - .offset:         234
        .size:           2
        .value_kind:     hidden_remainder_x
      - .offset:         236
        .size:           2
        .value_kind:     hidden_remainder_y
      - .offset:         238
        .size:           2
        .value_kind:     hidden_remainder_z
      - .offset:         256
        .size:           8
        .value_kind:     hidden_global_offset_x
      - .offset:         264
        .size:           8
        .value_kind:     hidden_global_offset_y
      - .offset:         272
        .size:           8
        .value_kind:     hidden_global_offset_z
      - .offset:         280
        .size:           2
        .value_kind:     hidden_grid_dims
      - .offset:         304
        .size:           8
        .value_kind:     hidden_multigrid_sync_arg
      - .offset:         336
        .size:           4
        .value_kind:     hidden_dynamic_lds_size
    .group_segment_fixed_size: 0
    .kernarg_segment_align: 8
    .kernarg_segment_size: 472
    .language:       OpenCL C
    .language_version:
      - 2
      - 0
    .max_flat_workgroup_size: 512
    .name:           _Z8fwd_mega6Params
    .private_segment_fixed_size: 0
    .sgpr_count:     108
    .sgpr_spill_count: 65
    .symbol:         _Z8fwd_mega6Params.kd
    .uniform_work_group_size: 1
    .uses_dynamic_stack: false
    .vgpr_count:     246
    .vgpr_spill_count: 0
    .wavefront_size: 64
